# speedup vs baseline: 1.0043x; 1.0043x over previous
.LBB0_265:
	s_or_b64 exec, exec, s[0:1]
	v_or_b32_e32 v130, s4, v147
	v_add_u32_e32 v132, v130, v150
	v_ashrrev_i32_e32 v133, 31, v132
	v_lshl_add_u64 v[134:135], v[132:133], 2, s[10:11]
	global_load_dword v130, v[134:135], off
	global_load_dword v200, v[134:135], off offset:512
	v_or_b32_e32 v138, 16, v132
	v_or_b32_e32 v136, 32, v132
	v_or_b32_e32 v134, 48, v132
	v_ashrrev_i32_e32 v139, 31, v138
	v_ashrrev_i32_e32 v137, 31, v136
	v_ashrrev_i32_e32 v135, 31, v134
	v_lshl_add_u64 v[140:141], v[138:139], 2, s[10:11]
	v_lshl_add_u64 v[142:143], v[136:137], 2, s[10:11]
	v_lshl_add_u64 v[154:155], v[134:135], 2, s[10:11]
	global_load_dword v152, v[140:141], off
	global_load_dword v151, v[142:143], off
	global_load_dword v150, v[154:155], off
	global_load_dword v201, v[140:141], off offset:512
	global_load_dword v202, v[142:143], off offset:512
	global_load_dword v203, v[154:155], off offset:512
	v_lshlrev_b32_e32 v140, 5, v145
	v_lshlrev_b32_e32 v143, 3, v146
	v_or3_b32 v153, v140, s74, v143
	s_cmp_gt_u32 s73, 3
	s_mov_b64 s[4:5], -1
	s_cselect_b64 s[0:1], -1, 0
	s_cmp_lt_u32 s73, 4
	s_waitcnt vmcnt(0)
	v_fmamk_f32 v130, v130, 0x3a800000, v148
	v_mul_f32_e32 v140, 0x4b800000, v130
	v_cmp_gt_f32_e32 vcc, s71, v130
	s_nop 1
	v_cndmask_b32_e32 v130, v130, v140, vcc
	v_rsq_f32_e32 v130, v130
	v_lshlrev_b64 v[140:141], 11, v[132:133]
	v_lshl_add_u64 v[140:141], s[20:21], 0, v[140:141]
	v_mul_f32_e32 v142, 0x45800000, v130
	v_cndmask_b32_e32 v142, v130, v142, vcc
	v_pk_mul_f32 v[144:145], v[122:123], v[142:143] op_sel_hi:[1,0]
	v_pk_mul_f32 v[146:147], v[124:125], v[142:143] op_sel_hi:[1,0]
	v_pk_mul_f32 v[126:127], v[126:127], v[142:143] op_sel_hi:[1,0]
	v_pk_mul_f32 v[128:129], v[128:129], v[142:143] op_sel_hi:[1,0]
	v_lshlrev_b32_e32 v130, 1, v153
	s_cbranch_scc1 .LBB0_267
	v_mul_f32_e32 v122, 0xbfb8aa3b, v144
	v_mul_f32_e32 v123, 0xbfb8aa3b, v145
	v_mul_f32_e32 v124, 0xbfb8aa3b, v146
	v_mul_f32_e32 v125, 0xbfb8aa3b, v147
	v_mul_f32_e32 v154, 0xbfb8aa3b, v126
	v_mul_f32_e32 v155, 0xbfb8aa3b, v127
	v_mul_f32_e32 v156, 0xbfb8aa3b, v128
	v_mul_f32_e32 v157, 0xbfb8aa3b, v129
	v_exp_f32_e32 v122, v122
	v_exp_f32_e32 v123, v123
	v_exp_f32_e32 v124, v124
	v_exp_f32_e32 v125, v125
	v_exp_f32_e32 v154, v154
	v_exp_f32_e32 v155, v155
	v_exp_f32_e32 v156, v156
	v_exp_f32_e32 v157, v157
	v_add_f32_e32 v122, 1.0, v122
	v_add_f32_e32 v123, 1.0, v123
	v_add_f32_e32 v124, 1.0, v124
	v_add_f32_e32 v125, 1.0, v125
	v_add_f32_e32 v154, 1.0, v154
	v_add_f32_e32 v155, 1.0, v155
	v_add_f32_e32 v156, 1.0, v156
	v_add_f32_e32 v157, 1.0, v157
	v_rcp_f32_e32 v122, v122
	v_rcp_f32_e32 v123, v123
	v_rcp_f32_e32 v124, v124
	v_rcp_f32_e32 v125, v125
	v_rcp_f32_e32 v154, v154
	v_rcp_f32_e32 v155, v155
	v_rcp_f32_e32 v156, v156
	v_rcp_f32_e32 v157, v157
	v_pk_mul_f32 v[122:123], v[144:145], v[122:123]
	v_pk_mul_f32 v[124:125], v[146:147], v[124:125]
	v_pk_mul_f32 v[154:155], v[126:127], v[154:155]
	v_pk_mul_f32 v[156:157], v[128:129], v[156:157]
	v_cvt_pk_bf16_f32 v122, v122, v123
	v_cvt_pk_bf16_f32 v123, v124, v125
	v_cvt_pk_bf16_f32 v124, v154, v155
	v_cvt_pk_bf16_f32 v125, v156, v157
	v_lshl_add_u64 v[154:155], v[140:141], 0, v[130:131]
	s_mov_b64 s[4:5], 0
	global_store_dwordx4 v[154:155], v[122:125], off offset:-2048

.LBB0_297:
	s_nop 1
	v_add_u32_e32 v72, 0x80, v132
	v_ashrrev_i32_e32 v73, 31, v72
	v_lshl_add_u64 v[66:67], v[72:73], 2, s[10:11]
	v_mov_b32_e32 v81, v200
	v_add_u32_e32 v70, 0x90, v132
	v_add_u32_e32 v68, 0xa0, v132
	v_add_u32_e32 v66, 0xb0, v132
	v_ashrrev_i32_e32 v71, 31, v70
	v_ashrrev_i32_e32 v69, 31, v68
	v_ashrrev_i32_e32 v67, 31, v66
	v_lshl_add_u64 v[74:75], v[70:71], 2, s[10:11]
	v_lshl_add_u64 v[76:77], v[68:69], 2, s[10:11]
	v_lshl_add_u64 v[82:83], v[66:67], 2, s[10:11]
	v_mov_b32_e32 v80, v201
	v_mov_b32_e32 v79, v202
	v_mov_b32_e32 v78, v203
	v_lshlrev_b64 v[82:83], 11, v[72:73]
	s_mov_b64 s[0:1], -1
	s_and_b64 vcc, exec, s[4:5]
	s_nop 0
	v_fmamk_f32 v74, v81, 0x3a800000, v148
	v_mul_f32_e32 v75, 0x4b800000, v74
	v_cmp_gt_f32_e64 s[6:7], s71, v74
	s_nop 1
	v_cndmask_b32_e64 v74, v74, v75, s[6:7]
	v_rsq_f32_e32 v74, v74
	s_nop 0
	v_mul_f32_e32 v75, 0x45800000, v74
	v_cndmask_b32_e64 v74, v74, v75, s[6:7]
	v_pk_mul_f32 v[76:77], v[58:59], v[74:75] op_sel_hi:[1,0]
	v_pk_mul_f32 v[60:61], v[60:61], v[74:75] op_sel_hi:[1,0]
	v_pk_mul_f32 v[62:63], v[62:63], v[74:75] op_sel_hi:[1,0]
	v_pk_mul_f32 v[64:65], v[64:65], v[74:75] op_sel_hi:[1,0]
	v_lshl_add_u64 v[58:59], s[20:21], 0, v[82:83]
	s_cbranch_vccnz .LBB0_299
	v_mul_f32_e32 v75, 0xbfb8aa3b, v76
	v_exp_f32_e32 v75, v75
	v_mul_f32_e32 v81, 0xbfb8aa3b, v77
	v_exp_f32_e32 v81, v81
	v_mul_f32_e32 v83, 0xbfb8aa3b, v61
	v_add_f32_e32 v75, 1.0, v75
	v_rcp_f32_e32 v82, v75
	v_mul_f32_e32 v75, 0xbfb8aa3b, v60
	v_exp_f32_e32 v75, v75
	v_exp_f32_e32 v85, v83
	v_add_f32_e32 v81, 1.0, v81
	v_rcp_f32_e32 v83, v81
	v_add_f32_e32 v75, 1.0, v75
	v_mul_f32_e32 v81, 0xbfb8aa3b, v62
	v_rcp_f32_e32 v84, v75
	v_add_f32_e32 v75, 1.0, v85
	v_exp_f32_e32 v81, v81
	v_mul_f32_e32 v85, 0xbfb8aa3b, v63
	v_exp_f32_e32 v87, v85
	v_rcp_f32_e32 v85, v75
	v_add_f32_e32 v75, 1.0, v81
	v_mul_f32_e32 v81, 0xbfb8aa3b, v64
	v_rcp_f32_e32 v86, v75
	v_add_f32_e32 v75, 1.0, v87
	v_exp_f32_e32 v81, v81
	v_mul_f32_e32 v87, 0xbfb8aa3b, v65
	v_exp_f32_e32 v89, v87
	v_rcp_f32_e32 v87, v75
	v_add_f32_e32 v75, 1.0, v81
	v_rcp_f32_e32 v88, v75
	v_add_f32_e32 v75, 1.0, v89
	v_rcp_f32_e32 v89, v75
	v_pk_mul_f32 v[82:83], v[76:77], v[82:83]
	v_pk_mul_f32 v[84:85], v[60:61], v[84:85]
	v_pk_mul_f32 v[86:87], v[62:63], v[86:87]
	v_pk_mul_f32 v[88:89], v[64:65], v[88:89]
	v_cvt_pk_bf16_f32 v82, v82, v83
	v_cvt_pk_bf16_f32 v83, v84, v85
	v_cvt_pk_bf16_f32 v84, v86, v87
	v_cvt_pk_bf16_f32 v85, v88, v89
	v_lshl_add_u64 v[86:87], v[58:59], 0, v[130:131]
	s_mov_b64 s[0:1], 0
	global_store_dwordx4 v[86:87], v[82:85], off offset:-2048

.LBB0_305:
	s_nop 0
	v_fmamk_f32 v50, v80, 0x3a800000, v148
	v_mul_f32_e32 v51, 0x4b800000, v50
	v_cmp_gt_f32_e32 vcc, s71, v50
	v_lshlrev_b64 v[54:55], 11, v[70:71]
	s_mov_b64 s[0:1], -1
	v_cndmask_b32_e32 v50, v50, v51, vcc
	v_rsq_f32_e32 v50, v50
	s_nop 0
	v_mul_f32_e32 v51, 0x45800000, v50
	v_cndmask_b32_e32 v50, v50, v51, vcc
	v_pk_mul_f32 v[46:47], v[46:47], v[50:51] op_sel_hi:[1,0]
	v_pk_mul_f32 v[48:49], v[48:49], v[50:51] op_sel_hi:[1,0]
	v_pk_mul_f32 v[52:53], v[42:43], v[50:51] op_sel_hi:[1,0]
	v_pk_mul_f32 v[44:45], v[44:45], v[50:51] op_sel_hi:[1,0]
	s_and_b64 vcc, exec, s[4:5]
	v_lshl_add_u64 v[42:43], s[20:21], 0, v[54:55]
	s_cbranch_vccnz .LBB0_307
	v_mul_f32_e32 v51, 0xbfb8aa3b, v46
	v_exp_f32_e32 v51, v51
	v_mul_f32_e32 v54, 0xbfb8aa3b, v47
	v_exp_f32_e32 v54, v54
	v_mul_f32_e32 v56, 0xbfb8aa3b, v49
	v_add_f32_e32 v51, 1.0, v51
	v_exp_f32_e32 v57, v56
	v_add_f32_e32 v55, 1.0, v54
	v_rcp_f32_e32 v54, v51
	v_mul_f32_e32 v51, 0xbfb8aa3b, v48
	v_exp_f32_e32 v51, v51
	v_rcp_f32_e32 v55, v55
	s_mov_b64 s[0:1], 0
	v_add_f32_e32 v51, 1.0, v51
	v_rcp_f32_e32 v56, v51
	v_add_f32_e32 v51, 1.0, v57
	v_mul_f32_e32 v57, 0xbfb8aa3b, v52
	v_exp_f32_e32 v58, v57
	v_mul_f32_e32 v57, 0xbfb8aa3b, v53
	v_exp_f32_e32 v59, v57
	v_rcp_f32_e32 v57, v51
	v_add_f32_e32 v51, 1.0, v58
	v_rcp_f32_e32 v58, v51
	v_add_f32_e32 v51, 1.0, v59
	v_mul_f32_e32 v59, 0xbfb8aa3b, v44
	v_exp_f32_e32 v60, v59
	v_mul_f32_e32 v59, 0xbfb8aa3b, v45
	v_exp_f32_e32 v61, v59
	v_rcp_f32_e32 v59, v51
	v_add_f32_e32 v51, 1.0, v60
	v_rcp_f32_e32 v60, v51
	v_add_f32_e32 v51, 1.0, v61
	v_rcp_f32_e32 v61, v51
	v_pk_mul_f32 v[54:55], v[46:47], v[54:55]
	v_pk_mul_f32 v[56:57], v[48:49], v[56:57]
	v_pk_mul_f32 v[58:59], v[52:53], v[58:59]
	v_pk_mul_f32 v[60:61], v[44:45], v[60:61]
	v_cvt_pk_bf16_f32 v54, v54, v55
	v_cvt_pk_bf16_f32 v55, v56, v57
	v_cvt_pk_bf16_f32 v56, v58, v59
	v_cvt_pk_bf16_f32 v57, v60, v61
	v_lshl_add_u64 v[58:59], v[42:43], 0, v[130:131]
	global_store_dwordx4 v[58:59], v[54:57], off offset:-2048

.LBB0_313:
	s_nop 0
	v_fmamk_f32 v34, v79, 0x3a800000, v148
	v_mul_f32_e32 v35, 0x4b800000, v34
	v_cmp_gt_f32_e32 vcc, s71, v34
	v_lshlrev_b64 v[38:39], 11, v[68:69]
	s_mov_b64 s[0:1], -1
	v_cndmask_b32_e32 v34, v34, v35, vcc
	v_rsq_f32_e32 v34, v34
	s_nop 0
	v_mul_f32_e32 v35, 0x45800000, v34
	v_cndmask_b32_e32 v34, v34, v35, vcc
	v_pk_mul_f32 v[30:31], v[30:31], v[34:35] op_sel_hi:[1,0]
	v_pk_mul_f32 v[32:33], v[32:33], v[34:35] op_sel_hi:[1,0]
	v_pk_mul_f32 v[36:37], v[26:27], v[34:35] op_sel_hi:[1,0]
	v_pk_mul_f32 v[28:29], v[28:29], v[34:35] op_sel_hi:[1,0]
	s_and_b64 vcc, exec, s[4:5]
	v_lshl_add_u64 v[26:27], s[20:21], 0, v[38:39]
	s_cbranch_vccnz .LBB0_315
	v_mul_f32_e32 v35, 0xbfb8aa3b, v30
	v_exp_f32_e32 v35, v35
	v_mul_f32_e32 v38, 0xbfb8aa3b, v31
	v_exp_f32_e32 v38, v38
	v_mul_f32_e32 v40, 0xbfb8aa3b, v33
	v_add_f32_e32 v35, 1.0, v35
	v_exp_f32_e32 v41, v40
	v_add_f32_e32 v39, 1.0, v38
	v_rcp_f32_e32 v38, v35
	v_mul_f32_e32 v35, 0xbfb8aa3b, v32
	v_exp_f32_e32 v35, v35
	v_rcp_f32_e32 v39, v39
	s_mov_b64 s[0:1], 0
	v_add_f32_e32 v35, 1.0, v35
	v_rcp_f32_e32 v40, v35
	v_add_f32_e32 v35, 1.0, v41
	v_mul_f32_e32 v41, 0xbfb8aa3b, v36
	v_exp_f32_e32 v42, v41
	v_mul_f32_e32 v41, 0xbfb8aa3b, v37
	v_exp_f32_e32 v43, v41
	v_rcp_f32_e32 v41, v35
	v_add_f32_e32 v35, 1.0, v42
	v_rcp_f32_e32 v42, v35
	v_add_f32_e32 v35, 1.0, v43
	v_mul_f32_e32 v43, 0xbfb8aa3b, v28
	v_exp_f32_e32 v44, v43
	v_mul_f32_e32 v43, 0xbfb8aa3b, v29
	v_exp_f32_e32 v45, v43
	v_rcp_f32_e32 v43, v35
	v_add_f32_e32 v35, 1.0, v44
	v_rcp_f32_e32 v44, v35
	v_add_f32_e32 v35, 1.0, v45
	v_rcp_f32_e32 v45, v35
	v_pk_mul_f32 v[38:39], v[30:31], v[38:39]
	v_pk_mul_f32 v[40:41], v[32:33], v[40:41]
	v_pk_mul_f32 v[42:43], v[36:37], v[42:43]
	v_pk_mul_f32 v[44:45], v[28:29], v[44:45]
	v_cvt_pk_bf16_f32 v38, v38, v39
	v_cvt_pk_bf16_f32 v39, v40, v41
	v_cvt_pk_bf16_f32 v40, v42, v43
	v_cvt_pk_bf16_f32 v41, v44, v45
	v_lshl_add_u64 v[42:43], v[26:27], 0, v[130:131]
	global_store_dwordx4 v[42:43], v[38:41], off offset:-2048

.LBB0_321:
	s_nop 0
	v_fmamk_f32 v18, v78, 0x3a800000, v148
	v_mul_f32_e32 v19, 0x4b800000, v18
	v_cmp_gt_f32_e32 vcc, s71, v18
	v_lshlrev_b64 v[22:23], 11, v[66:67]
	s_mov_b64 s[0:1], -1
	v_cndmask_b32_e32 v18, v18, v19, vcc
	v_rsq_f32_e32 v18, v18
	s_nop 0
	v_mul_f32_e32 v19, 0x45800000, v18
	v_cndmask_b32_e32 v18, v18, v19, vcc
	v_pk_mul_f32 v[14:15], v[14:15], v[18:19] op_sel_hi:[1,0]
	v_pk_mul_f32 v[16:17], v[16:17], v[18:19] op_sel_hi:[1,0]
	v_pk_mul_f32 v[20:21], v[10:11], v[18:19] op_sel_hi:[1,0]
	v_pk_mul_f32 v[12:13], v[12:13], v[18:19] op_sel_hi:[1,0]
	s_and_b64 vcc, exec, s[4:5]
	v_lshl_add_u64 v[10:11], s[20:21], 0, v[22:23]
	s_cbranch_vccnz .LBB0_323
	v_mul_f32_e32 v19, 0xbfb8aa3b, v14
	v_exp_f32_e32 v19, v19
	v_mul_f32_e32 v22, 0xbfb8aa3b, v15
	v_exp_f32_e32 v22, v22
	v_mul_f32_e32 v24, 0xbfb8aa3b, v17
	v_add_f32_e32 v19, 1.0, v19
	v_exp_f32_e32 v25, v24
	v_add_f32_e32 v23, 1.0, v22
	v_rcp_f32_e32 v22, v19
	v_mul_f32_e32 v19, 0xbfb8aa3b, v16
	v_exp_f32_e32 v19, v19
	v_rcp_f32_e32 v23, v23
	s_mov_b64 s[0:1], 0
	v_add_f32_e32 v19, 1.0, v19
	v_rcp_f32_e32 v24, v19
	v_add_f32_e32 v19, 1.0, v25
	v_mul_f32_e32 v25, 0xbfb8aa3b, v20
	v_exp_f32_e32 v26, v25
	v_mul_f32_e32 v25, 0xbfb8aa3b, v21
	v_exp_f32_e32 v27, v25
	v_rcp_f32_e32 v25, v19
	v_add_f32_e32 v19, 1.0, v26
	v_rcp_f32_e32 v26, v19
	v_add_f32_e32 v19, 1.0, v27
	v_mul_f32_e32 v27, 0xbfb8aa3b, v12
	v_exp_f32_e32 v28, v27
	v_mul_f32_e32 v27, 0xbfb8aa3b, v13
	v_exp_f32_e32 v29, v27
	v_rcp_f32_e32 v27, v19
	v_add_f32_e32 v19, 1.0, v28
	v_rcp_f32_e32 v28, v19
	v_add_f32_e32 v19, 1.0, v29
	v_rcp_f32_e32 v29, v19
	v_pk_mul_f32 v[22:23], v[14:15], v[22:23]
	v_pk_mul_f32 v[24:25], v[16:17], v[24:25]
	v_pk_mul_f32 v[26:27], v[20:21], v[26:27]
	v_pk_mul_f32 v[28:29], v[12:13], v[28:29]
	v_cvt_pk_bf16_f32 v22, v22, v23
	v_cvt_pk_bf16_f32 v23, v24, v25
	v_cvt_pk_bf16_f32 v24, v26, v27
	v_cvt_pk_bf16_f32 v25, v28, v29
	v_lshl_add_u64 v[26:27], v[10:11], 0, v[130:131]
	global_store_dwordx4 v[26:27], v[22:25], off offset:-2048
